# v30 + P5 start stagger by XCD (8 levels x s_sleep 11)
# speedup vs baseline: 1.0031x; 1.0013x over previous
.LBB0_1040:
	s_or_b64 exec, exec, s[0:1]
	v_readlane_b32 s0, v246, 28
	v_mov_b32_e32 v9, v214
	v_readlane_b32 s1, v246, 29
	s_waitcnt lgkmcnt(0)
	s_barrier
	s_and_b64 vcc, exec, s[0:1]
	v_readfirstlane_b32 s5, v9
	s_cbranch_vccnz .LBB0_1056
	s_lshr_b32 s0, s90, 0
	s_and_b32 s0, s0, 7
	s_cmp_eq_u32 s0, 0
	s_cbranch_scc1 .Lstag5_done

.Lstag5_done:
	v_lshlrev_b32_e32 v0, 4, v9
	v_add_u32_e32 v1, 0x2000, v0
	v_ashrrev_i32_e32 v2, 31, v1
	v_lshrrev_b32_e32 v2, 22, v2
	v_add_u32_e32 v2, v1, v2
	v_ashrrev_i32_e32 v8, 10, v2
	v_mul_i32_i24_e32 v2, 0x400, v8
	v_sub_u32_e32 v1, v1, v2
	v_lshrrev_b32_e32 v2, 4, v1
	v_bitop3_b32 v1, v2, v1, 32 bitop3:0x6c
	v_ashrrev_i32_e32 v2, 31, v1
	v_lshrrev_b32_e32 v2, 26, v2
	v_add_u32_e32 v2, v1, v2
	v_lshlrev_b32_e32 v3, 3, v8
	v_ashrrev_i32_e32 v10, 6, v2
	v_and_b32_e32 v3, -16, v3
	v_add_u32_e32 v3, v10, v3
	v_and_b32_e32 v4, 3, v10
	s_mov_b32 s0, 0x1fffe0
	v_lshrrev_b32_e32 v5, 2, v3
	v_lshlrev_b32_e32 v6, 1, v3
	v_and_b32_e32 v2, 0xc0, v2
	v_and_or_b32 v4, v3, s0, v4
	v_and_b32_e32 v5, 4, v5
	v_and_b32_e32 v6, 24, v6
	v_sub_u32_e32 v1, v1, v2
	v_mov_b32_e32 v2, 1
	v_or3_b32 v4, v4, v5, v6
	v_lshlrev_b32_e32 v5, 5, v8
	v_ashrrev_i16_sdwa v1, v2, sext(v1) dst_sel:DWORD dst_unused:UNUSED_PAD src0_sel:DWORD src1_sel:BYTE_0
	v_and_b32_e32 v5, 32, v5
	v_bfe_i32 v11, v1, 0, 16
	v_add_lshl_u32 v1, v5, v11, 1
	v_lshl_add_u32 v128, v4, 11, v1
	v_lshl_add_u32 v130, v3, 11, v1
	v_bfe_i32 v1, v9, 27, 1
	v_lshrrev_b32_e32 v1, 22, v1
	v_add_u32_e32 v1, v0, v1
	v_and_b32_e32 v1, 0xfffffc00, v1
	v_sub_u32_e32 v0, v0, v1
	v_lshrrev_b32_e32 v1, 4, v0
	v_ashrrev_i32_e32 v3, 31, v9
	v_bitop3_b32 v0, v1, v0, 32 bitop3:0x6c
	v_lshrrev_b32_e32 v3, 26, v3
	v_ashrrev_i32_e32 v1, 31, v0
	v_add_u32_e32 v3, v9, v3
	v_lshrrev_b32_e32 v1, 26, v1
	v_ashrrev_i32_e32 v13, 6, v3
	v_add_u32_e32 v1, v0, v1
	v_lshlrev_b32_e32 v3, 3, v13
	s_add_u32 s26, s82, 0x14800000
	v_ashrrev_i32_e32 v12, 6, v1
	v_and_b32_e32 v3, -16, v3
	s_addc_u32 s27, s83, 0
	v_add_u32_e32 v3, v12, v3
	v_and_b32_e32 v4, 3, v12
	s_ashr_i32 s29, s90, 31
	v_and_or_b32 v4, v3, s0, v4
	s_lshr_b32 s0, s29, 29
	s_add_i32 s0, s90, s0
	s_ashr_i32 s10, s5, 6
	s_ashr_i32 s1, s0, 3
	s_and_b32 s0, s0, -8
	s_ashr_i32 s12, s5, 8
	s_lshl_b32 s28, s10, 10
	s_sub_i32 s0, s90, s0
	s_cmp_lt_i32 s0, 0
	s_movk_i32 s30, 0x161
	s_cselect_b32 s2, s30, 0x160
	s_mul_i32 s0, s0, s2
	s_add_i32 s0, s0, s1
	s_mul_hi_i32 s1, s0, 0x2e8ba2e9
	s_lshr_b32 s2, s1, 31
	s_ashr_i32 s1, s1, 5
	s_add_i32 s1, s1, s2
	s_lshl_b32 s2, s1, 3
	s_mulk_i32 s1, 0xb0
	s_sub_i32 s0, s0, s1
	s_sext_i32_i16 s1, s0
	s_bfe_u32 s1, s1, 0x3001c
	s_add_i32 s1, s0, s1
	s_sext_i32_i16 s3, s1
	s_and_b32 s1, s1, 0xfff8
	s_sub_i32 s0, s0, s1
	s_sext_i32_i16 s0, s0
	v_lshrrev_b32_e32 v5, 2, v3
	v_lshlrev_b32_e32 v6, 1, v3
	v_and_b32_e32 v1, 0xc0, v1
	s_lshr_b32 s4, s3, 3
	s_add_i32 s0, s2, s0
	v_and_b32_e32 v5, 4, v5
	v_and_b32_e32 v6, 24, v6
	v_sub_u32_e32 v0, v0, v1
	s_ashr_i32 s1, s0, 31
	s_bfe_i64 s[2:3], s[4:5], 0x100000
	v_or3_b32 v4, v4, v5, v6
	v_lshlrev_b32_e32 v5, 5, v13
	v_ashrrev_i16_sdwa v0, v2, sext(v0) dst_sel:DWORD dst_unused:UNUSED_PAD src0_sel:DWORD src1_sel:BYTE_0
	s_lshl_b64 s[8:9], s[0:1], 19
	s_lshl_b64 s[2:3], s[2:3], 19
	v_and_b32_e32 v5, 32, v5
	v_bfe_i32 v14, v0, 0, 16
	s_add_u32 s2, s26, s2
	v_add_lshl_u32 v0, v5, v14, 1
	s_addc_u32 s3, s27, s3
	s_add_i32 s31, s28, 0
	v_lshl_add_u32 v132, v4, 11, v0
	s_add_i32 m0, s31, 0x10000
	v_lshl_add_u32 v134, v3, 11, v0
	global_load_lds_dwordx4 v132, s[2:3]
	s_add_i32 m0, s31, 0x12000
	s_add_u32 s14, s2, 0x40000
	global_load_lds_dwordx4 v128, s[2:3]
	s_addc_u32 s15, s3, 0
	s_add_i32 m0, s31, 0x14000
	v_mov_b32_e32 v133, 0
	global_load_lds_dwordx4 v132, s[14:15]
	s_add_i32 m0, s31, 0x16000
	v_mov_b32_e32 v129, v133
	global_load_lds_dwordx4 v128, s[14:15]
	v_readlane_b32 s14, v246, 30
	v_readlane_b32 s15, v246, 31
	s_add_u32 s22, s14, s8
	s_addc_u32 s23, s15, s9
	s_add_i32 s33, s31, 0x2000
	s_mov_b32 m0, s31
	s_add_u32 s8, s22, 0x40000
	global_load_lds_dwordx4 v134, s[22:23]
	s_mov_b32 m0, s33
	s_addc_u32 s9, s23, 0
	s_add_i32 s34, s31, 0x4000
	global_load_lds_dwordx4 v130, s[22:23]
	s_mov_b32 m0, s34
	s_add_i32 s35, s31, 0x6000
	global_load_lds_dwordx4 v134, s[8:9]
	s_mov_b32 m0, s35
	v_mov_b32_e32 v135, v133
	global_load_lds_dwordx4 v130, s[8:9]
	v_mov_b32_e32 v131, v133
	s_cmp_eq_u32 s12, 1
	s_mov_b32 s36, 0
	v_lshl_add_u64 v[6:7], s[2:3], 0, v[132:133]
	v_lshl_add_u64 v[4:5], s[2:3], 0, v[128:129]
	v_lshl_add_u64 v[0:1], s[22:23], 0, v[134:135]
	s_cselect_b64 s[8:9], -1, 0
	s_cmp_lg_u32 s12, 1
	v_lshl_add_u64 v[2:3], s[22:23], 0, v[130:131]
	s_cbranch_scc1 .LBB0_1043
	s_barrier
